# diff HTSP: cross-half max exchange only in rare rescale path (check on per-lane max), compare issued early
# speedup vs baseline: 1.0524x; 1.0005x over previous
.LBB0_800:
	s_or_b32 s90, s10, s23
	s_lshl_b64 s[12:13], s[90:91], 1
	v_lshl_add_u64 v[2:3], v[186:187], 0, s[12:13]
	v_mov_b32_e32 v20, v194
	global_load_dwordx4 v[114:117], v[2:3], off
	global_load_dwordx4 v[118:121], v[2:3], off offset:32
	global_load_dwordx4 v[122:125], v[2:3], off offset:64
	global_load_dwordx4 v[126:129], v[2:3], off offset:96
	s_xor_b64 s[8:9], s[8:9], -1
	v_lshrrev_b32_e32 v0, 2, v20
	v_and_b32_e32 v0, 0x3ffffe, v0
	v_lshlrev_b32_e32 v6, 4, v20
	s_add_u32 s12, s25, s12
	v_and_b32_e32 v183, 0x70, v6
	v_mul_u32_u24_e32 v0, 0xc00, v0
	s_addc_u32 s13, s26, s13
	v_or_b32_e32 v0, v0, v183
	v_ashrrev_i32_e32 v21, 3, v20
	v_add_u32_e32 v246, 0x30000, v0
	global_load_dwordx4 v[2:5], v246, s[12:13] offset:2048
	v_and_b32_e32 v205, 0xf0, v6
	v_and_b32_e32 v6, 0x3ffffe, v21
	v_mul_u32_u24_e32 v6, 0xc00, v6
	v_or_b32_e32 v16, v6, v205
	global_load_dwordx4 v[6:9], v16, s[2:3]
	v_add_u32_e32 v18, 0x30000, v16
	global_load_dwordx4 v[10:13], v18, s[2:3]
	s_mov_b32 s100, 0xfffd0000
	s_mov_b32 s101, -1
	v_lshl_add_u64 v[248:249], s[12:13], 0, v[0:1]
	v_lshl_add_u64 v[248:249], v[248:249], 0, s[100:101]
	global_load_dwordx4 v[242:245], v[248:249], off offset:2048
	v_mul_lo_u32 v206, v21, s88
	v_add3_u32 v21, 0, v206, v183
	s_movk_i32 s11, 0x140
	v_lshl_add_u64 v[14:15], s[12:13], 0, v[0:1]
	s_add_i32 s90, s24, s10
	v_mov_b32_e32 v19, v1
	v_mov_b32_e32 v17, v1
	v_lshl_add_u64 v[192:193], s[6:7], 0, v[18:19]
	v_lshl_add_u64 v[190:191], s[6:7], 0, v[16:17]
	v_mov_b32_e32 v212, 0
	s_mov_b32 s29, 0
	v_mov_b32_e32 v66, 0
	v_mov_b32_e32 v67, v212
	v_mov_b32_e32 v68, v212
	v_mov_b32_e32 v69, v212
	v_mov_b32_e32 v70, v212
	v_mov_b32_e32 v71, v212
	v_mov_b32_e32 v72, v212
	v_mov_b32_e32 v73, v212
	v_mov_b32_e32 v74, v212
	v_mov_b32_e32 v75, v212
	v_mov_b32_e32 v76, v212
	v_mov_b32_e32 v77, v212
	v_mov_b32_e32 v78, v212
	v_mov_b32_e32 v79, v212
	v_mov_b32_e32 v80, v212
	v_mov_b32_e32 v81, v212
	s_waitcnt vmcnt(3)
	ds_write_b128 v21, v[2:5]
	v_lshrrev_b32_e32 v2, 4, v20
	v_mul_lo_u32 v207, v2, s11
	v_add3_u32 v2, 0, v205, v207
	s_mov_b32 s11, 0x90000
	s_waitcnt vmcnt(2)
	ds_write_b128 v2, v[6:9] offset:9216
	s_waitcnt vmcnt(1)
	ds_write_b128 v2, v[10:13] offset:19456
	s_waitcnt vmcnt(0)
	ds_write_b128 v21, v[242:245] offset:29696
	v_add_co_u32_e32 v2, vcc, s11, v14
	s_lshl_b64 s[10:11], s[90:91], 1
	s_nop 0
	v_addc_co_u32_e32 v3, vcc, 0, v15, vcc
	global_load_dwordx4 v[130:133], v[2:3], off offset:2048
	global_load_dwordx4 v[134:137], v16, s[4:5]
	global_load_dwordx4 v[138:141], v18, s[4:5]
	v_and_b32_e32 v2, 31, v20
	v_bfe_u32 v3, v20, 5, 1
	v_mul_u32_u24_e32 v208, 0x90, v2
	v_bfe_u32 v2, v20, 2, 2
	v_lshl_or_b32 v2, v3, 2, v2
	v_lshlrev_b32_e32 v209, 4, v3
	v_mul_u32_u24_e32 v210, 0x140, v2
	v_and_b32_e32 v2, 16, v20
	v_lshlrev_b32_e32 v3, 2, v20
	s_add_u32 s10, s27, s10
	v_and_or_b32 v2, v3, 12, v2
	s_addc_u32 s11, s28, s11
	v_mov_b32_e32 v14, v1
	v_mov_b32_e32 v15, v1
	v_lshlrev_b32_e32 v211, 1, v2
	v_lshl_add_u64 v[188:189], s[10:11], 0, v[0:1]
	s_mov_b32 s98, 0x30000
	s_mov_b32 s99, 0
	v_lshl_add_u64 v[188:189], v[188:189], 0, s[98:99]
	v_mov_b32_e32 v0, v1
	v_mov_b32_e32 v2, v1
	v_mov_b32_e32 v3, v1
	v_mov_b32_e32 v4, v1
	v_mov_b32_e32 v5, v1
	v_mov_b32_e32 v6, v1
	v_mov_b32_e32 v7, v1
	v_mov_b32_e32 v8, v1
	v_mov_b32_e32 v9, v1
	v_mov_b32_e32 v10, v1
	v_mov_b32_e32 v11, v1
	v_mov_b32_e32 v12, v1
	v_mov_b32_e32 v13, v1
	v_mov_b64_e32 v[64:65], v[14:15]
	v_mov_b64_e32 v[48:49], v[14:15]
	v_mov_b64_e32 v[32:33], v[14:15]
	v_mov_b64_e32 v[62:63], v[12:13]
	v_mov_b64_e32 v[60:61], v[10:11]
	v_mov_b64_e32 v[58:59], v[8:9]
	v_mov_b64_e32 v[56:57], v[6:7]
	v_mov_b64_e32 v[54:55], v[4:5]
	v_mov_b64_e32 v[52:53], v[2:3]
	v_mov_b64_e32 v[50:51], v[0:1]
	v_mov_b64_e32 v[46:47], v[12:13]
	v_mov_b64_e32 v[44:45], v[10:11]
	v_mov_b64_e32 v[42:43], v[8:9]
	v_mov_b64_e32 v[40:41], v[6:7]
	v_mov_b64_e32 v[38:39], v[4:5]
	v_mov_b64_e32 v[36:37], v[2:3]
	v_mov_b64_e32 v[34:35], v[0:1]
	v_mov_b64_e32 v[30:31], v[12:13]
	v_mov_b64_e32 v[28:29], v[10:11]
	v_mov_b64_e32 v[26:27], v[8:9]
	v_mov_b64_e32 v[24:25], v[6:7]
	v_mov_b64_e32 v[22:23], v[4:5]
	v_mov_b64_e32 v[20:21], v[2:3]
	v_mov_b64_e32 v[18:19], v[0:1]
	v_mov_b64_e32 v[16:17], v[14:15]
	s_mov_b64 s[10:11], 0
	v_mov_b64_e32 v[14:15], v[12:13]
	v_mov_b64_e32 v[12:13], v[10:11]
	v_mov_b64_e32 v[10:11], v[8:9]
	v_mov_b64_e32 v[8:9], v[6:7]
	v_mov_b64_e32 v[6:7], v[4:5]
	v_mov_b64_e32 v[4:5], v[2:3]
	v_mov_b64_e32 v[2:3], v[0:1]
	v_mov_b32_e32 v0, 0
	s_waitcnt lgkmcnt(0)
	s_barrier
	s_movk_i32 s12, 0x7400
	v_add3_u32 v222, s12, v208, v209
	ds_read_b128 v[142:145], v222 offset:4608
	ds_read_b128 v[146:149], v222 offset:4640
	ds_read_b128 v[150:153], v222 offset:4672
	ds_read_b128 v[154:157], v222 offset:4704
	s_setprio 1
	s_waitcnt lgkmcnt(3)
	v_mfma_f32_32x32x16_bf16 v[98:113], v[142:145], v[114:117], v[66:81]
	s_waitcnt lgkmcnt(2)
	v_mfma_f32_32x32x16_bf16 v[98:113], v[146:149], v[118:121], v[98:113]
	s_waitcnt lgkmcnt(1)
	v_mfma_f32_32x32x16_bf16 v[98:113], v[150:153], v[122:125], v[98:113]
	s_waitcnt lgkmcnt(0)
	v_mfma_f32_32x32x16_bf16 v[98:113], v[154:157], v[126:129], v[98:113]
	s_setprio 0
	s_nop 15
	v_max3_f32 v223, v98, v99, v100
	v_max3_f32 v224, v101, v102, v103
	v_max3_f32 v223, v223, v104, v105
	v_max3_f32 v224, v224, v106, v107
	v_max3_f32 v223, v223, v108, v109
	v_max3_f32 v224, v224, v110, v111
	v_max3_f32 v223, v223, v112, v113
	v_max_f32_e32 v223, v223, v224
	v_cmp_lt_f32_e32 vcc, s61, v223
.Ld_loop:
	s_and_b32 s30, s29, 1
	s_mul_i32 s12, s30, 0x7400
	v_add3_u32 v222, s12, v208, v209
	v_add_u32_e32 v213, s12, v210
	v_add_u32_e32 v213, v213, v211
	s_cmp_eq_u32 s10, 0
	s_cselect_b64 s[16:17], -1, 0
	s_cmp_lg_u32 s10, 0
	s_cselect_b64 s[18:19], -1, 0
	s_waitcnt lgkmcnt(0)
	s_barrier
	ds_read_b128 v[142:145], v222 offset:0
	ds_read_b128 v[146:149], v222 offset:32
	ds_read_b128 v[150:153], v222 offset:64
	ds_read_b128 v[154:157], v222 offset:96
	ds_read_b64_tr_b16 v[226:227], v213 offset:9216
	ds_read_b64_tr_b16 v[230:231], v213 offset:9280
	ds_read_b64_tr_b16 v[234:235], v213 offset:9344
	ds_read_b64_tr_b16 v[238:239], v213 offset:9408
	ds_read_b64_tr_b16 v[228:229], v213 offset:11776
	ds_read_b64_tr_b16 v[232:233], v213 offset:11840
	ds_read_b64_tr_b16 v[236:237], v213 offset:11904
	ds_read_b64_tr_b16 v[240:241], v213 offset:11968
	s_or_b64 s[20:21], vcc, s[16:17]
	s_cmp_lg_u64 s[20:21], 0
	s_cbranch_scc1 .Ld_rareA
.Ld_goA:
	s_setprio 1
	s_waitcnt lgkmcnt(11)
	v_mfma_f32_32x32x16_bf16 v[82:97], v[142:145], v[114:117], v[66:81]
	v_exp_f32_e32 v98, v98
	v_exp_f32_e32 v99, v99
	s_waitcnt lgkmcnt(10)
	v_mfma_f32_32x32x16_bf16 v[82:97], v[146:149], v[118:121], v[82:97]
	v_exp_f32_e32 v100, v100
	v_exp_f32_e32 v101, v101
	v_cvt_pk_bf16_f32 v214, v98, v99
	s_waitcnt lgkmcnt(9)
	v_mfma_f32_32x32x16_bf16 v[82:97], v[150:153], v[122:125], v[82:97]
	v_exp_f32_e32 v102, v102
	v_exp_f32_e32 v103, v103
	v_cvt_pk_bf16_f32 v215, v100, v101
	s_waitcnt lgkmcnt(8)
	v_mfma_f32_32x32x16_bf16 v[82:97], v[154:157], v[126:129], v[82:97]
	v_exp_f32_e32 v104, v104
	v_exp_f32_e32 v105, v105
	v_cvt_pk_bf16_f32 v216, v102, v103
	v_cvt_pk_bf16_f32 v217, v104, v105
	ds_read_b64_tr_b16 v[142:143], v213 offset:14336
	ds_read_b64_tr_b16 v[146:147], v213 offset:14400
	ds_read_b64_tr_b16 v[150:151], v213 offset:14464
	ds_read_b64_tr_b16 v[154:155], v213 offset:14528
	ds_read_b64_tr_b16 v[144:145], v213 offset:16896
	ds_read_b64_tr_b16 v[148:149], v213 offset:16960
	ds_read_b64_tr_b16 v[152:153], v213 offset:17024
	ds_read_b64_tr_b16 v[156:157], v213 offset:17088
	s_waitcnt lgkmcnt(11)
	v_mfma_f32_32x32x16_bf16 v[50:65], v[226:229], v[214:217], v[50:65]
	v_exp_f32_e32 v106, v106
	v_exp_f32_e32 v107, v107
	v_add_f32_e32 v248, v98, v100
	s_waitcnt lgkmcnt(10)
	v_mfma_f32_32x32x16_bf16 v[34:49], v[230:233], v[214:217], v[34:49]
	v_exp_f32_e32 v108, v108
	v_exp_f32_e32 v109, v109
	v_cvt_pk_bf16_f32 v218, v106, v107
	v_add_f32_e32 v249, v99, v101
	s_waitcnt lgkmcnt(9)
	v_mfma_f32_32x32x16_bf16 v[18:33], v[234:237], v[214:217], v[18:33]
	v_exp_f32_e32 v110, v110
	v_exp_f32_e32 v111, v111
	v_cvt_pk_bf16_f32 v219, v108, v109
	v_add_f32_e32 v248, v248, v102
	s_waitcnt lgkmcnt(8)
	v_mfma_f32_32x32x16_bf16 v[2:17], v[238:241], v[214:217], v[2:17]
	v_exp_f32_e32 v112, v112
	v_exp_f32_e32 v113, v113
	v_cvt_pk_bf16_f32 v220, v110, v111
	v_cvt_pk_bf16_f32 v221, v112, v113
	ds_read_b128 v[226:229], v222 offset:4608
	ds_read_b128 v[230:233], v222 offset:4640
	ds_read_b128 v[234:237], v222 offset:4672
	ds_read_b128 v[238:241], v222 offset:4704
	s_waitcnt lgkmcnt(7)
	v_mfma_f32_32x32x16_bf16 v[50:65], v[142:145], v[218:221], v[50:65]
	v_max3_f32 v223, v82, v83, v84
	v_max3_f32 v224, v85, v86, v87
	v_add_f32_e32 v249, v249, v103
	v_add_f32_e32 v248, v248, v104
	v_add_f32_e32 v249, v249, v105
	s_waitcnt lgkmcnt(6)
	v_mfma_f32_32x32x16_bf16 v[34:49], v[146:149], v[218:221], v[34:49]
	v_max3_f32 v223, v223, v88, v89
	v_max3_f32 v224, v224, v90, v91
	v_add_f32_e32 v248, v248, v106
	v_add_f32_e32 v249, v249, v107
	v_add_f32_e32 v248, v248, v108
	s_waitcnt lgkmcnt(5)
	v_mfma_f32_32x32x16_bf16 v[18:33], v[150:153], v[218:221], v[18:33]
	v_max3_f32 v223, v223, v92, v93
	v_max3_f32 v224, v224, v94, v95
	v_add_f32_e32 v249, v249, v109
	v_add_f32_e32 v248, v248, v110
	v_add_f32_e32 v249, v249, v111
	s_waitcnt lgkmcnt(4)
	v_mfma_f32_32x32x16_bf16 v[2:17], v[154:157], v[218:221], v[2:17]
	s_setprio 0
	v_max3_f32 v223, v223, v96, v97
	v_max_f32_e32 v223, v223, v224
	v_cmp_lt_f32_e32 vcc, s61, v223
	ds_read_b64_tr_b16 v[142:143], v213 offset:19456
	ds_read_b64_tr_b16 v[146:147], v213 offset:19520
	ds_read_b64_tr_b16 v[150:151], v213 offset:19584
	ds_read_b64_tr_b16 v[154:155], v213 offset:19648
	ds_read_b64_tr_b16 v[144:145], v213 offset:22016
	ds_read_b64_tr_b16 v[148:149], v213 offset:22080
	ds_read_b64_tr_b16 v[152:153], v213 offset:22144
	ds_read_b64_tr_b16 v[156:157], v213 offset:22208
	v_add_f32_e32 v248, v248, v112
	v_add_f32_e32 v249, v249, v113
	v_add_f32_e32 v248, v248, v249
	v_add_f32_e32 v0, v0, v248
	s_cmp_lg_u64 vcc, 0
	s_cbranch_scc1 .Ld_rareB
.Ld_goB:
	s_setprio 1
	s_waitcnt lgkmcnt(11)
	v_mfma_f32_32x32x16_bf16 v[98:113], v[226:229], v[114:117], v[66:81]
	v_exp_f32_e32 v82, v82
	v_exp_f32_e32 v83, v83
	s_waitcnt lgkmcnt(10)
	v_mfma_f32_32x32x16_bf16 v[98:113], v[230:233], v[118:121], v[98:113]
	v_exp_f32_e32 v84, v84
	v_exp_f32_e32 v85, v85
	v_cvt_pk_bf16_f32 v214, v82, v83
	s_waitcnt lgkmcnt(9)
	v_mfma_f32_32x32x16_bf16 v[98:113], v[234:237], v[122:125], v[98:113]
	v_exp_f32_e32 v86, v86
	v_exp_f32_e32 v87, v87
	v_cvt_pk_bf16_f32 v215, v84, v85
	s_waitcnt lgkmcnt(8)
	v_mfma_f32_32x32x16_bf16 v[98:113], v[238:241], v[126:129], v[98:113]
	v_exp_f32_e32 v88, v88
	v_exp_f32_e32 v89, v89
	v_cvt_pk_bf16_f32 v216, v86, v87
	v_cvt_pk_bf16_f32 v217, v88, v89
	ds_read_b64_tr_b16 v[226:227], v213 offset:24576
	ds_read_b64_tr_b16 v[230:231], v213 offset:24640
	ds_read_b64_tr_b16 v[234:235], v213 offset:24704
	ds_read_b64_tr_b16 v[238:239], v213 offset:24768
	ds_read_b64_tr_b16 v[228:229], v213 offset:27136
	ds_read_b64_tr_b16 v[232:233], v213 offset:27200
	ds_read_b64_tr_b16 v[236:237], v213 offset:27264
	ds_read_b64_tr_b16 v[240:241], v213 offset:27328
	s_waitcnt lgkmcnt(11)
	v_mfma_f32_32x32x16_bf16 v[50:65], v[142:145], v[214:217], v[50:65]
	v_exp_f32_e32 v90, v90
	v_exp_f32_e32 v91, v91
	v_add_f32_e32 v248, v82, v84
	s_waitcnt lgkmcnt(10)
	v_mfma_f32_32x32x16_bf16 v[34:49], v[146:149], v[214:217], v[34:49]
	v_exp_f32_e32 v92, v92
	v_exp_f32_e32 v93, v93
	v_cvt_pk_bf16_f32 v218, v90, v91
	v_add_f32_e32 v249, v83, v85
	s_waitcnt lgkmcnt(9)
	v_mfma_f32_32x32x16_bf16 v[18:33], v[150:153], v[214:217], v[18:33]
	v_exp_f32_e32 v94, v94
	v_exp_f32_e32 v95, v95
	v_cvt_pk_bf16_f32 v219, v92, v93
	v_add_f32_e32 v248, v248, v86
	s_waitcnt lgkmcnt(8)
	v_mfma_f32_32x32x16_bf16 v[2:17], v[154:157], v[214:217], v[2:17]
	v_exp_f32_e32 v96, v96
	v_exp_f32_e32 v97, v97
	v_cvt_pk_bf16_f32 v220, v94, v95
	v_cvt_pk_bf16_f32 v221, v96, v97
	s_waitcnt lgkmcnt(3)
	v_mfma_f32_32x32x16_bf16 v[50:65], v[226:229], v[218:221], v[50:65]
	v_max3_f32 v223, v98, v99, v100
	v_max3_f32 v224, v101, v102, v103
	v_add_f32_e32 v249, v249, v87
	v_add_f32_e32 v248, v248, v88
	v_add_f32_e32 v249, v249, v89
	s_waitcnt lgkmcnt(2)
	v_mfma_f32_32x32x16_bf16 v[34:49], v[230:233], v[218:221], v[34:49]
	v_max3_f32 v223, v223, v104, v105
	v_max3_f32 v224, v224, v106, v107
	v_add_f32_e32 v248, v248, v90
	v_add_f32_e32 v249, v249, v91
	v_add_f32_e32 v248, v248, v92
	s_waitcnt lgkmcnt(1)
	v_mfma_f32_32x32x16_bf16 v[18:33], v[234:237], v[218:221], v[18:33]
	v_max3_f32 v223, v223, v108, v109
	v_max3_f32 v224, v224, v110, v111
	v_add_f32_e32 v249, v249, v93
	v_add_f32_e32 v248, v248, v94
	v_add_f32_e32 v249, v249, v95
	s_waitcnt lgkmcnt(0)
	v_mfma_f32_32x32x16_bf16 v[2:17], v[238:241], v[218:221], v[2:17]
	s_setprio 0
	v_max3_f32 v223, v223, v112, v113
	v_max_f32_e32 v223, v223, v224
	v_cmp_lt_f32_e32 vcc, s61, v223
	v_add_f32_e32 v248, v248, v96
	v_add_f32_e32 v249, v249, v97
	v_add_f32_e32 v248, v248, v249
	v_add_f32_e32 v0, v0, v248
	s_cmp_eq_u32 s10, 0x17a0000
	s_cbranch_scc1 .Ld_next
	s_xor_b32 s12, s30, 1
	s_mulk_i32 s12, 0x7400
	v_add3_u32 v246, s12, v206, v183
	s_waitcnt vmcnt(2)
	ds_write_b128 v246, v[130:133]
	v_add3_u32 v246, s12, v205, v207
	s_cmp_gt_u32 s29, 61
	s_waitcnt vmcnt(1)
	ds_write_b128 v246, v[134:137] offset:9216
	s_waitcnt vmcnt(0)
	ds_write_b128 v246, v[138:141] offset:19456
	s_cbranch_scc1 .Ld_next
	v_lshl_add_u64 v[130:131], v[188:189], 0, s[10:11]
	v_lshl_add_u64 v[134:135], v[190:191], 0, s[10:11]
	v_lshl_add_u64 v[138:139], v[192:193], 0, s[10:11]
	global_load_dwordx4 v[130:133], v[130:131], off
	s_nop 0
	global_load_dwordx4 v[134:137], v[134:135], off
	s_nop 0
	global_load_dwordx4 v[138:141], v[138:139], off

.Ld_rareA:
	s_nop 15
	v_mov_b32_e32 v225, v223
	s_nop 1
	v_permlane32_swap_b32_e32 v223, v225
	v_max_f32_e32 v225, v223, v225
	v_max_f32_e32 v66, v225, v225
	s_andn2_b64 vcc, exec, s[18:19]
	v_max_f32_e32 v66, 0, v66
	s_cbranch_vccnz .Ld_rareA2
	v_exp_f32_e64 v68, -v66
	s_nop 0
	v_mul_f32_e32 v0, v0, v68
	v_pk_mul_f32 v[64:65], v[64:65], v[68:69] op_sel_hi:[1,0]
	v_pk_mul_f32 v[62:63], v[62:63], v[68:69] op_sel_hi:[1,0]
	v_pk_mul_f32 v[60:61], v[60:61], v[68:69] op_sel_hi:[1,0]
	v_pk_mul_f32 v[58:59], v[58:59], v[68:69] op_sel_hi:[1,0]
	v_pk_mul_f32 v[56:57], v[56:57], v[68:69] op_sel_hi:[1,0]
	v_pk_mul_f32 v[54:55], v[54:55], v[68:69] op_sel_hi:[1,0]
	v_pk_mul_f32 v[52:53], v[52:53], v[68:69] op_sel_hi:[1,0]
	v_pk_mul_f32 v[50:51], v[50:51], v[68:69] op_sel_hi:[1,0]
	v_pk_mul_f32 v[48:49], v[48:49], v[68:69] op_sel_hi:[1,0]
	v_pk_mul_f32 v[46:47], v[46:47], v[68:69] op_sel_hi:[1,0]
	v_pk_mul_f32 v[44:45], v[44:45], v[68:69] op_sel_hi:[1,0]
	v_pk_mul_f32 v[42:43], v[42:43], v[68:69] op_sel_hi:[1,0]
	v_pk_mul_f32 v[40:41], v[40:41], v[68:69] op_sel_hi:[1,0]
	v_pk_mul_f32 v[38:39], v[38:39], v[68:69] op_sel_hi:[1,0]
	v_pk_mul_f32 v[36:37], v[36:37], v[68:69] op_sel_hi:[1,0]
	v_pk_mul_f32 v[34:35], v[34:35], v[68:69] op_sel_hi:[1,0]
	v_pk_mul_f32 v[32:33], v[32:33], v[68:69] op_sel_hi:[1,0]
	v_pk_mul_f32 v[30:31], v[30:31], v[68:69] op_sel_hi:[1,0]
	v_pk_mul_f32 v[28:29], v[28:29], v[68:69] op_sel_hi:[1,0]
	v_pk_mul_f32 v[26:27], v[26:27], v[68:69] op_sel_hi:[1,0]
	v_pk_mul_f32 v[24:25], v[24:25], v[68:69] op_sel_hi:[1,0]
	v_pk_mul_f32 v[22:23], v[22:23], v[68:69] op_sel_hi:[1,0]
	v_pk_mul_f32 v[20:21], v[20:21], v[68:69] op_sel_hi:[1,0]
	v_pk_mul_f32 v[18:19], v[18:19], v[68:69] op_sel_hi:[1,0]
	v_pk_mul_f32 v[16:17], v[16:17], v[68:69] op_sel_hi:[1,0]
	v_pk_mul_f32 v[14:15], v[14:15], v[68:69] op_sel_hi:[1,0]
	v_pk_mul_f32 v[12:13], v[12:13], v[68:69] op_sel_hi:[1,0]
	v_pk_mul_f32 v[10:11], v[10:11], v[68:69] op_sel_hi:[1,0]
	v_pk_mul_f32 v[8:9], v[8:9], v[68:69] op_sel_hi:[1,0]
	v_pk_mul_f32 v[6:7], v[6:7], v[68:69] op_sel_hi:[1,0]
	v_pk_mul_f32 v[4:5], v[4:5], v[68:69] op_sel_hi:[1,0]
	v_pk_mul_f32 v[2:3], v[2:3], v[68:69] op_sel_hi:[1,0]

.Ld_rareB:
	s_nop 15
	v_mov_b32_e32 v225, v223
	s_nop 1
	v_permlane32_swap_b32_e32 v223, v225
	v_max_f32_e32 v225, v223, v225
	v_max_f32_e32 v66, v225, v225
	v_max_f32_e32 v66, 0, v66
	v_exp_f32_e64 v68, -v66
	s_nop 0
	v_mul_f32_e32 v0, v0, v68
	v_pk_mul_f32 v[64:65], v[64:65], v[68:69] op_sel_hi:[1,0]
	v_pk_mul_f32 v[62:63], v[62:63], v[68:69] op_sel_hi:[1,0]
	v_pk_mul_f32 v[60:61], v[60:61], v[68:69] op_sel_hi:[1,0]
	v_pk_mul_f32 v[58:59], v[58:59], v[68:69] op_sel_hi:[1,0]
	v_pk_mul_f32 v[56:57], v[56:57], v[68:69] op_sel_hi:[1,0]
	v_pk_mul_f32 v[54:55], v[54:55], v[68:69] op_sel_hi:[1,0]
	v_pk_mul_f32 v[52:53], v[52:53], v[68:69] op_sel_hi:[1,0]
	v_pk_mul_f32 v[50:51], v[50:51], v[68:69] op_sel_hi:[1,0]
	v_pk_mul_f32 v[48:49], v[48:49], v[68:69] op_sel_hi:[1,0]
	v_pk_mul_f32 v[46:47], v[46:47], v[68:69] op_sel_hi:[1,0]
	v_pk_mul_f32 v[44:45], v[44:45], v[68:69] op_sel_hi:[1,0]
	v_pk_mul_f32 v[42:43], v[42:43], v[68:69] op_sel_hi:[1,0]
	v_pk_mul_f32 v[40:41], v[40:41], v[68:69] op_sel_hi:[1,0]
	v_pk_mul_f32 v[38:39], v[38:39], v[68:69] op_sel_hi:[1,0]
	v_pk_mul_f32 v[36:37], v[36:37], v[68:69] op_sel_hi:[1,0]
	v_pk_mul_f32 v[34:35], v[34:35], v[68:69] op_sel_hi:[1,0]
	v_pk_mul_f32 v[32:33], v[32:33], v[68:69] op_sel_hi:[1,0]
	v_pk_mul_f32 v[30:31], v[30:31], v[68:69] op_sel_hi:[1,0]
	v_pk_mul_f32 v[28:29], v[28:29], v[68:69] op_sel_hi:[1,0]
	v_pk_mul_f32 v[26:27], v[26:27], v[68:69] op_sel_hi:[1,0]
	v_pk_mul_f32 v[24:25], v[24:25], v[68:69] op_sel_hi:[1,0]
	v_pk_mul_f32 v[22:23], v[22:23], v[68:69] op_sel_hi:[1,0]
	v_pk_mul_f32 v[20:21], v[20:21], v[68:69] op_sel_hi:[1,0]
	v_pk_mul_f32 v[18:19], v[18:19], v[68:69] op_sel_hi:[1,0]
	v_pk_mul_f32 v[16:17], v[16:17], v[68:69] op_sel_hi:[1,0]
	v_pk_mul_f32 v[14:15], v[14:15], v[68:69] op_sel_hi:[1,0]
	v_pk_mul_f32 v[12:13], v[12:13], v[68:69] op_sel_hi:[1,0]
	v_pk_mul_f32 v[10:11], v[10:11], v[68:69] op_sel_hi:[1,0]
	v_pk_mul_f32 v[8:9], v[8:9], v[68:69] op_sel_hi:[1,0]
	v_pk_mul_f32 v[6:7], v[6:7], v[68:69] op_sel_hi:[1,0]
	v_pk_mul_f32 v[4:5], v[4:5], v[68:69] op_sel_hi:[1,0]
	v_pk_mul_f32 v[2:3], v[2:3], v[68:69] op_sel_hi:[1,0]
	v_add_f32_e32 v212, v212, v66
	v_xor_b32_e32 v81, 0x80000000, v212
	v_pk_add_f32 v[82:83], v[82:83], v[66:67] op_sel_hi:[1,0] neg_lo:[0,1] neg_hi:[0,1]
	v_pk_add_f32 v[84:85], v[84:85], v[66:67] op_sel_hi:[1,0] neg_lo:[0,1] neg_hi:[0,1]
	v_pk_add_f32 v[86:87], v[86:87], v[66:67] op_sel_hi:[1,0] neg_lo:[0,1] neg_hi:[0,1]
	v_pk_add_f32 v[88:89], v[88:89], v[66:67] op_sel_hi:[1,0] neg_lo:[0,1] neg_hi:[0,1]
	v_pk_add_f32 v[90:91], v[90:91], v[66:67] op_sel_hi:[1,0] neg_lo:[0,1] neg_hi:[0,1]
	v_pk_add_f32 v[92:93], v[92:93], v[66:67] op_sel_hi:[1,0] neg_lo:[0,1] neg_hi:[0,1]
	v_pk_add_f32 v[94:95], v[94:95], v[66:67] op_sel_hi:[1,0] neg_lo:[0,1] neg_hi:[0,1]
	v_pk_add_f32 v[96:97], v[96:97], v[66:67] op_sel_hi:[1,0] neg_lo:[0,1] neg_hi:[0,1]
	v_mov_b32_e32 v80, v81
	v_mov_b32_e32 v79, v81
	v_mov_b32_e32 v78, v81
	v_mov_b32_e32 v77, v81
	v_mov_b32_e32 v76, v81
	v_mov_b32_e32 v75, v81
	v_mov_b32_e32 v74, v81
	v_mov_b32_e32 v73, v81
	v_mov_b32_e32 v72, v81
	v_mov_b32_e32 v71, v81
	v_mov_b32_e32 v70, v81
	v_mov_b32_e32 v69, v81
	v_mov_b32_e32 v68, v81
	v_mov_b32_e32 v67, v81
	v_mov_b32_e32 v66, v81
	s_branch .Ld_goB
